# P6 row sum of squares via DPP row_shr/row_bcast + readlane instead of six serial ds_bpermute hops; on top of v81
# baseline (speedup 1.0000x reference)
; __device__ __forceinline__ void sample_finalize(const Args& a) {
;     ...
;     for (int r = gw; r < MS; r += NGW) {
;         f32x4 v[4]; float ss = 0.f;
; #pragma unroll
;         for (int j = 0; j < 4; ++j) { const int col = 4 * lane + 256 * j;
;             f32x4 p = *(const f32x4*)(part + (size_t)r * DM + col);
; #pragma unroll
;             for (int ks = 1; ks < 4; ++ks) p += *(const f32x4*)(part + ((size_t)ks * MS + r) * DM + col);
;             v[j] = *(const f32x4*)(a.in[1] + (size_t)r * DM + col) + *(const f32x4*)(gatef + (16 + (r >> 5)) * DM + col) * p;
;             ss += (v[j][0] * v[j][0] + v[j][1] * v[j][1]) + (v[j][2] * v[j][2] + v[j][3] * v[j][3]); }
.LBB0_1314:
	v_lshl_add_u64 v[90:91], s[2:3], 0, v[0:1]
	v_add_co_u32_e32 v50, vcc, 0x1e900000, v90
	v_lshl_add_u64 v[30:31], s[6:7], 0, v[0:1]
	s_nop 0
	v_addc_co_u32_e32 v51, vcc, 0, v91, vcc
	v_add_co_u32_e32 v92, vcc, 0x1ed00000, v90
	s_and_b32 s8, s10, 0xfffffc00
	global_load_dwordx4 v[14:17], v[30:31], off
	global_load_dwordx4 v[18:21], v[30:31], off offset:1024
	global_load_dwordx4 v[22:25], v[30:31], off offset:2048
	global_load_dwordx4 v[26:29], v[30:31], off offset:3072
	v_addc_co_u32_e32 v93, vcc, 0, v91, vcc
	global_load_dwordx4 v[30:33], v[50:51], off
	global_load_dwordx4 v[34:37], v[50:51], off offset:1024
	global_load_dwordx4 v[38:41], v[50:51], off offset:2048
	global_load_dwordx4 v[42:45], v[50:51], off offset:3072
	global_load_dwordx4 v[46:49], v[92:93], off
	s_addk_i32 s8, 0x4000
	v_add_co_u32_e32 v94, vcc, 0x1f100000, v90
	s_ashr_i32 s9, s8, 31
	s_nop 0
	v_addc_co_u32_e32 v95, vcc, 0, v91, vcc
	v_lshl_add_u64 v[110:111], s[8:9], 2, v[4:5]
	v_add_co_u32_e32 v112, vcc, 0x1f500000, v90
	global_load_dwordx4 v[50:53], v[92:93], off offset:1024
	global_load_dwordx4 v[54:57], v[92:93], off offset:2048
	global_load_dwordx4 v[58:61], v[110:111], off
	global_load_dwordx4 v[62:65], v[110:111], off offset:1024
	global_load_dwordx4 v[66:69], v[92:93], off offset:3072
	global_load_dwordx4 v[70:73], v[110:111], off offset:2048
	global_load_dwordx4 v[74:77], v[94:95], off
	global_load_dwordx4 v[78:81], v[94:95], off offset:1024
	global_load_dwordx4 v[82:85], v[94:95], off offset:2048
	global_load_dwordx4 v[86:89], v[94:95], off offset:3072
	v_addc_co_u32_e32 v113, vcc, 0, v91, vcc
	global_load_dwordx4 v[90:93], v[112:113], off
	global_load_dwordx4 v[94:97], v[112:113], off offset:1024
	global_load_dwordx4 v[98:101], v[112:113], off offset:2048
	global_load_dwordx4 v[102:105], v[112:113], off offset:3072
	global_load_dwordx4 v[106:109], v[110:111], off offset:3072
	s_add_i32 s8, s0, 0x8000
	global_load_dwordx4 v[110:113], v[2:3], off
	global_load_dwordx4 v[116:119], v[2:3], off offset:1024
	global_load_dwordx4 v[120:123], v[2:3], off offset:2048
	global_load_dwordx4 v[124:127], v[2:3], off offset:3072
	s_ashr_i32 s9, s8, 31
	s_lshl_b64 s[8:9], s[8:9], 12
	v_lshl_add_u64 v[114:115], v[6:7], 0, s[8:9]
	s_add_i32 s0, s0, s34
	s_add_i32 s10, s10, s11
	s_add_u32 s2, s2, s4
	s_addc_u32 s3, s3, s5
	s_add_u32 s6, s6, s4
	s_addc_u32 s7, s7, s5
	s_cmpk_lt_i32 s0, 0x400
	s_waitcnt vmcnt(19)
	v_pk_add_f32 v[32:33], v[32:33], v[48:49]
	v_pk_add_f32 v[30:31], v[30:31], v[46:47]
	s_waitcnt vmcnt(18)
	v_pk_add_f32 v[36:37], v[36:37], v[52:53]
	v_pk_add_f32 v[34:35], v[34:35], v[50:51]
	s_waitcnt vmcnt(17)
	v_pk_add_f32 v[40:41], v[40:41], v[56:57]
	v_pk_add_f32 v[38:39], v[38:39], v[54:55]
	s_waitcnt vmcnt(14)
	v_pk_add_f32 v[42:43], v[42:43], v[66:67]
	s_waitcnt vmcnt(12)
	v_pk_add_f32 v[32:33], v[32:33], v[76:77]
	v_pk_add_f32 v[30:31], v[30:31], v[74:75]
	s_waitcnt vmcnt(11)
	v_pk_add_f32 v[36:37], v[36:37], v[80:81]
	v_pk_add_f32 v[34:35], v[34:35], v[78:79]
	s_waitcnt vmcnt(8)
	v_pk_add_f32 v[32:33], v[32:33], v[92:93]
	v_pk_add_f32 v[30:31], v[30:31], v[90:91]
	s_waitcnt vmcnt(7)
	v_pk_add_f32 v[36:37], v[36:37], v[96:97]
	v_pk_add_f32 v[34:35], v[34:35], v[94:95]
	v_pk_add_f32 v[44:45], v[44:45], v[68:69]
	v_pk_add_f32 v[40:41], v[40:41], v[84:85]
	v_pk_add_f32 v[38:39], v[38:39], v[82:83]
	v_pk_add_f32 v[42:43], v[42:43], v[86:87]
	v_pk_fma_f32 v[16:17], v[32:33], v[60:61], v[16:17]
	v_pk_fma_f32 v[14:15], v[30:31], v[58:59], v[14:15]
	v_pk_fma_f32 v[20:21], v[36:37], v[64:65], v[20:21]
	v_pk_fma_f32 v[18:19], v[34:35], v[62:63], v[18:19]
	v_pk_add_f32 v[44:45], v[44:45], v[88:89]
	s_waitcnt vmcnt(6)
; __device__ __forceinline__ void sample_finalize(const Args& a) {
;     ...
;         const float rr = rsqrtf(wave_sum(ss) * (1.f / DM) + EPS);
; #pragma unroll
;         for (int j = 0; j < 4; ++j) { const int col = 4 * lane + 256 * j; *(f32x4*)(a.out + (size_t)(MP + r) * DM + col) = v[j] * rr * *(const f32x4*)(a.in[18] + col); }
	v_pk_add_f32 v[40:41], v[40:41], v[100:101]
	v_pk_add_f32 v[38:39], v[38:39], v[98:99]
	s_waitcnt vmcnt(5)
	v_pk_add_f32 v[42:43], v[42:43], v[102:103]
	v_pk_mul_f32 v[30:31], v[16:17], v[16:17]
	v_pk_mul_f32 v[32:33], v[14:15], v[14:15]
	v_pk_mul_f32 v[34:35], v[20:21], v[20:21]
	v_pk_mul_f32 v[36:37], v[18:19], v[18:19]
	v_pk_add_f32 v[44:45], v[44:45], v[104:105]
	v_pk_fma_f32 v[24:25], v[40:41], v[72:73], v[24:25]
	v_pk_fma_f32 v[22:23], v[38:39], v[70:71], v[22:23]
	s_waitcnt vmcnt(4)
	v_pk_fma_f32 v[26:27], v[42:43], v[106:107], v[26:27]
	v_pk_mov_b32 v[42:43], v[32:33], v[30:31] op_sel:[1,0]
	v_mov_b32_e32 v33, v31
	v_pk_mov_b32 v[30:31], v[36:37], v[34:35] op_sel:[1,0]
	v_mov_b32_e32 v37, v35
	v_pk_fma_f32 v[28:29], v[44:45], v[108:109], v[28:29]
	v_mul_f32_e32 v41, v27, v27
	v_mul_f32_e32 v38, v23, v23
	v_mul_f32_e32 v40, v25, v25
	v_pk_add_f32 v[32:33], v[42:43], v[32:33]
	v_pk_add_f32 v[30:31], v[30:31], v[36:37]
	v_mul_f32_e32 v13, v26, v26
	v_mul_f32_e32 v44, v28, v28
	v_mul_f32_e32 v45, v29, v29
	v_pk_fma_f32 v[34:35], v[22:23], v[22:23], v[38:39] op_sel_hi:[1,1,0]
	v_pk_fma_f32 v[38:39], v[24:25], v[24:25], v[40:41] op_sel_hi:[1,1,0]
	v_pk_add_f32 v[32:33], v[32:33], v[32:33] op_sel:[0,1] op_sel_hi:[1,0]
	v_pk_add_f32 v[30:31], v[30:31], v[30:31] op_sel:[0,1] op_sel_hi:[1,0]
	v_mov_b32_e32 v35, v44
	v_mov_b32_e32 v39, v45
	v_mov_b32_e32 v33, v13
	v_mov_b32_e32 v31, v41
	v_pk_add_f32 v[34:35], v[34:35], v[38:39]
	v_pk_add_f32 v[30:31], v[32:33], v[30:31]
	s_nop 0
	v_pk_add_f32 v[30:31], v[30:31], v[34:35]
	s_nop 0
	v_add_f32_e32 v13, v30, v31
	s_nop 1
	v_add_f32_dpp v13, v13, v13 row_shr:1 row_mask:0xf bank_mask:0xf bound_ctrl:1
	s_nop 1
	v_add_f32_dpp v13, v13, v13 row_shr:2 row_mask:0xf bank_mask:0xf bound_ctrl:1
	s_nop 1
	v_add_f32_dpp v13, v13, v13 row_shr:4 row_mask:0xf bank_mask:0xf bound_ctrl:1
	s_nop 1
	v_add_f32_dpp v13, v13, v13 row_shr:8 row_mask:0xf bank_mask:0xf bound_ctrl:1
	s_nop 1
	v_add_f32_dpp v13, v13, v13 row_bcast:15 row_mask:0xa bank_mask:0xf
	s_nop 1
	v_add_f32_dpp v13, v13, v13 row_bcast:31 row_mask:0xc bank_mask:0xf
	s_nop 0
	v_readlane_b32 s98, v13, 63
	s_nop 1
	v_mov_b32_e32 v13, s98
	v_fmamk_f32 v13, v13, 0x3a800000, v12
	v_mul_f32_e32 v30, 0x4b800000, v13
	v_cmp_gt_f32_e32 vcc, s1, v13
	s_nop 1
	v_cndmask_b32_e32 v13, v13, v30, vcc
	v_rsq_f32_e32 v13, v13
	s_nop 0
	v_mul_f32_e32 v30, 0x45800000, v13
	v_cndmask_b32_e32 v30, v13, v30, vcc
	v_pk_mul_f32 v[14:15], v[14:15], v[30:31] op_sel_hi:[1,0]
	v_pk_mul_f32 v[16:17], v[16:17], v[30:31] op_sel_hi:[1,0]
	s_waitcnt vmcnt(0)
	v_pk_mul_f32 v[14:15], v[110:111], v[14:15]
	v_pk_mul_f32 v[16:17], v[112:113], v[16:17]
	global_store_dwordx4 v[114:115], v[14:17], off
	v_pk_mul_f32 v[20:21], v[20:21], v[30:31] op_sel_hi:[1,0]
	v_pk_mul_f32 v[18:19], v[18:19], v[30:31] op_sel_hi:[1,0]
	v_pk_mul_f32 v[16:17], v[118:119], v[20:21]
	v_pk_mul_f32 v[14:15], v[116:117], v[18:19]
	global_store_dwordx4 v[114:115], v[14:17], off offset:1024
	v_pk_mul_f32 v[18:19], v[24:25], v[30:31] op_sel_hi:[1,0]
	v_pk_mul_f32 v[20:21], v[22:23], v[30:31] op_sel_hi:[1,0]
	v_pk_mul_f32 v[16:17], v[122:123], v[18:19]
	v_pk_mul_f32 v[14:15], v[120:121], v[20:21]
	global_store_dwordx4 v[114:115], v[14:17], off offset:2048
	v_pk_mul_f32 v[18:19], v[28:29], v[30:31] op_sel_hi:[1,0]
	v_pk_mul_f32 v[20:21], v[26:27], v[30:31] op_sel_hi:[1,0]
	v_pk_mul_f32 v[16:17], v[126:127], v[18:19]
	v_pk_mul_f32 v[14:15], v[124:125], v[20:21]
	global_store_dwordx4 v[114:115], v[14:17], off offset:3072
	s_cbranch_scc1 .LBB0_1314
